# P1: per-round rotation of the tile-to-workgroup assignment within each XCD to balance gelu/silu tiles
# speedup vs baseline: 1.0084x; 1.0084x over previous
.LBB0_125:
	s_andn2_b64 vcc, exec, s[74:75]
	s_mov_b64 s[76:77], 0
	s_cbranch_vccnz .LBB0_127
	s_ashr_i32 s47, s50, 31
	s_lshr_b32 s47, s47, 29
	s_add_i32 s47, s50, s47
	s_ashr_i32 s49, s47, 3
	s_lshr_b32 s51, s49, 5
	s_and_b32 s56, s51, 1
	s_mul_i32 s56, s56, 12
	s_cmp_eq_u32 s51, 2
	s_cselect_b32 s56, 16, s56
	s_cmp_gt_u32 s51, 3
	s_cselect_b32 s56, 0, s56
	s_add_i32 s56, s56, s49
	s_and_b32 s56, s56, 31
	s_andn2_b32 s49, s49, 31
	s_or_b32 s49, s49, s56
	s_and_b32 s47, s47, -8
	s_sub_i32 s47, s50, s47
	s_cmp_lt_i32 s47, 0
	s_movk_i32 s50, 0x91
	s_cselect_b32 s50, s50, 0x90
	s_mul_i32 s47, s47, s50
	s_add_i32 s47, s47, s49
	s_mul_hi_i32 s49, s47, 0x38e38e39
	s_lshr_b32 s50, s49, 31
	s_ashr_i32 s49, s49, 3
	s_add_i32 s49, s49, s50
	s_lshl_b32 s50, s49, 1
	s_sub_i32 s51, 64, s50
	s_min_i32 s51, s51, 2
	s_abs_i32 s56, s51
	v_cvt_f32_u32_e32 v0, s56
	s_sub_i32 s71, 0, s56
	s_mul_i32 s49, s49, 36
	s_sub_i32 s47, s47, s49
	v_rcp_iflag_f32_e32 v0, v0
	s_abs_i32 s49, s47
	s_xor_b32 s70, s47, s51
	s_ashr_i32 s70, s70, 31
	v_mul_f32_e32 v0, 0x4f7ffffe, v0
	v_cvt_u32_f32_e32 v0, v0
	s_mov_b64 s[76:77], -1
	v_readfirstlane_b32 s72, v0
	s_mul_i32 s71, s71, s72
	s_mul_hi_u32 s71, s72, s71
	s_add_i32 s72, s72, s71
	s_mul_hi_u32 s71, s49, s72
	s_mul_i32 s72, s71, s56
	s_sub_i32 s49, s49, s72
	s_add_i32 s73, s71, 1
	s_sub_i32 s72, s49, s56
	s_cmp_ge_u32 s49, s56
	s_cselect_b32 s71, s73, s71
	s_cselect_b32 s49, s72, s49
	s_add_i32 s72, s71, 1
	s_cmp_ge_u32 s49, s56
	s_cselect_b32 s49, s72, s71
	s_xor_b32 s49, s49, s70
	s_sub_i32 s70, s49, s70
	s_mul_i32 s49, s70, s51
	s_sub_i32 s47, s47, s49
	s_add_i32 s72, s50, s47
	s_mov_b32 s56, s30
